# setprio: removed the back-to-back 'setprio 0; setprio 1' pair in the middle of every 32-MFMA segment
# speedup vs baseline: 1.0524x; 1.0002x over previous
.LBB0_180:
	ds_read_b128 v[152:155], v159
	ds_read_b128 v[162:165], v159 offset:1024
	ds_read_b128 v[166:169], v159 offset:2048
	ds_read_b128 v[170:173], v159 offset:3072
	ds_read_b128 v[174:177], v160
	ds_read_b128 v[178:181], v160 offset:1024
	ds_read_b128 v[182:185], v160 offset:2048
	ds_read_b128 v[186:189], v160 offset:3072
	s_add_u32 s4, s0, 0xfffc0080
	s_addc_u32 s5, s1, -1
	s_cmp_eq_u32 vcc_lo, 12
	s_cselect_b32 s83, s39, s5
	s_cselect_b32 s82, s38, s4
	s_cselect_b32 s5, s73, s79
	s_cselect_b32 s4, s72, s53
	v_lshl_add_u64 v[198:199], s[0:1], 0, v[144:145]
	s_add_i32 m0, s43, 0xc000
	ds_read_b128 v[190:193], v161
	ds_read_b128 v[194:197], v161 offset:1024
	ds_read_b128 v[202:205], v161 offset:2048
	ds_read_b128 v[206:209], v161 offset:3072
	ds_read_b128 v[210:213], v161 offset:4096
	ds_read_b128 v[214:217], v161 offset:5120
	ds_read_b128 v[218:221], v161 offset:6144
	ds_read_b128 v[222:225], v161 offset:7168
	global_load_lds_dwordx4 v[198:199], off
	v_lshl_add_u64 v[198:199], s[0:1], 0, v[146:147]
	s_add_i32 m0, s43, 0xe000
	s_nop 0
	global_load_lds_dwordx4 v[198:199], off
	s_waitcnt vmcnt(8)
	s_waitcnt lgkmcnt(0)
	s_barrier
	s_setprio 1
	s_waitcnt lgkmcnt(0)
	v_mfma_f32_16x16x32_bf16 v[124:127], v[152:155], v[190:193], v[124:127]
	v_mfma_f32_16x16x32_bf16 v[120:123], v[166:169], v[190:193], v[120:123]
	v_mfma_f32_16x16x32_bf16 v[108:111], v[152:155], v[202:205], v[108:111]
	v_mfma_f32_16x16x32_bf16 v[104:107], v[166:169], v[202:205], v[104:107]
	v_mfma_f32_16x16x32_bf16 v[92:95], v[152:155], v[210:213], v[92:95]
	v_mfma_f32_16x16x32_bf16 v[88:91], v[166:169], v[210:213], v[88:91]
	v_mfma_f32_16x16x32_bf16 v[76:79], v[152:155], v[218:221], v[76:79]
	v_mfma_f32_16x16x32_bf16 v[72:75], v[166:169], v[218:221], v[72:75]
	v_mfma_f32_16x16x32_bf16 v[124:127], v[162:165], v[194:197], v[124:127]
	v_mfma_f32_16x16x32_bf16 v[120:123], v[170:173], v[194:197], v[120:123]
	v_mfma_f32_16x16x32_bf16 v[108:111], v[162:165], v[206:209], v[108:111]
	v_mfma_f32_16x16x32_bf16 v[104:107], v[170:173], v[206:209], v[104:107]
	v_mfma_f32_16x16x32_bf16 v[92:95], v[162:165], v[214:217], v[92:95]
	v_mfma_f32_16x16x32_bf16 v[88:91], v[170:173], v[214:217], v[88:91]
	v_mfma_f32_16x16x32_bf16 v[76:79], v[162:165], v[222:225], v[76:79]
	v_mfma_f32_16x16x32_bf16 v[72:75], v[170:173], v[222:225], v[72:75]
	v_mfma_f32_16x16x32_bf16 v[116:119], v[174:177], v[190:193], v[116:119]
	v_mfma_f32_16x16x32_bf16 v[112:115], v[182:185], v[190:193], v[112:115]
	v_mfma_f32_16x16x32_bf16 v[100:103], v[174:177], v[202:205], v[100:103]
	v_mfma_f32_16x16x32_bf16 v[96:99], v[182:185], v[202:205], v[96:99]
	v_mfma_f32_16x16x32_bf16 v[84:87], v[174:177], v[210:213], v[84:87]
	v_mfma_f32_16x16x32_bf16 v[80:83], v[182:185], v[210:213], v[80:83]
	v_mfma_f32_16x16x32_bf16 v[68:71], v[174:177], v[218:221], v[68:71]
	v_mfma_f32_16x16x32_bf16 v[64:67], v[182:185], v[218:221], v[64:67]
	v_mfma_f32_16x16x32_bf16 v[116:119], v[178:181], v[194:197], v[116:119]
	v_mfma_f32_16x16x32_bf16 v[112:115], v[186:189], v[194:197], v[112:115]
	v_mfma_f32_16x16x32_bf16 v[100:103], v[178:181], v[206:209], v[100:103]
	v_mfma_f32_16x16x32_bf16 v[96:99], v[186:189], v[206:209], v[96:99]
	v_mfma_f32_16x16x32_bf16 v[84:87], v[178:181], v[214:217], v[84:87]
	v_mfma_f32_16x16x32_bf16 v[80:83], v[186:189], v[214:217], v[80:83]
	v_mfma_f32_16x16x32_bf16 v[68:71], v[178:181], v[222:225], v[68:71]
	v_mfma_f32_16x16x32_bf16 v[64:67], v[186:189], v[222:225], v[64:67]
	s_setprio 0
	s_barrier
	s_add_i32 s12, s9, s3
	v_lshl_add_u64 v[198:199], s[4:5], 0, v[132:133]
	s_mov_b32 m0, s12
	ds_read_b128 v[190:193], v161 offset:16384
	ds_read_b128 v[194:197], v161 offset:17408
	ds_read_b128 v[202:205], v161 offset:18432
	ds_read_b128 v[206:209], v161 offset:19456
	ds_read_b128 v[210:213], v161 offset:20480
	ds_read_b128 v[214:217], v161 offset:21504
	ds_read_b128 v[218:221], v161 offset:22528
	ds_read_b128 v[222:225], v161 offset:23552
	global_load_lds_dwordx4 v[198:199], off
	s_add_i32 m0, s12, 0x2000
	s_add_u32 s12, s4, 0x40000
	v_lshl_add_u64 v[226:227], s[4:5], 0, v[128:129]
	s_addc_u32 s13, s5, 0
	s_add_i32 vcc_hi, s10, s3
	global_load_lds_dwordx4 v[226:227], off
	v_lshl_add_u64 v[228:229], s[12:13], 0, v[132:133]
	s_mov_b32 m0, vcc_hi
	v_lshl_add_u64 v[230:231], s[82:83], 0, v[130:131]
	global_load_lds_dwordx4 v[228:229], off
	v_lshl_add_u64 v[228:229], s[12:13], 0, v[128:129]
	s_add_i32 m0, vcc_hi, 0x2000
	s_nop 0
	global_load_lds_dwordx4 v[228:229], off
	v_lshl_add_u64 v[228:229], s[82:83], 0, v[134:135]
	s_mov_b32 m0, s43
	s_nop 0
	global_load_lds_dwordx4 v[228:229], off
	s_mov_b32 m0, s75
	s_nop 0
	global_load_lds_dwordx4 v[230:231], off
	s_waitcnt vmcnt(8)
	s_waitcnt lgkmcnt(0)
	s_barrier
	s_setprio 1
	s_waitcnt lgkmcnt(0)
	v_mfma_f32_16x16x32_bf16 v[60:63], v[152:155], v[190:193], v[60:63]
	v_mfma_f32_16x16x32_bf16 v[56:59], v[166:169], v[190:193], v[56:59]
	v_mfma_f32_16x16x32_bf16 v[44:47], v[152:155], v[202:205], v[44:47]
	v_mfma_f32_16x16x32_bf16 v[40:43], v[166:169], v[202:205], v[40:43]
	v_mfma_f32_16x16x32_bf16 v[28:31], v[152:155], v[210:213], v[28:31]
	v_mfma_f32_16x16x32_bf16 v[24:27], v[166:169], v[210:213], v[24:27]
	v_mfma_f32_16x16x32_bf16 v[12:15], v[152:155], v[218:221], v[12:15]
	v_mfma_f32_16x16x32_bf16 v[8:11], v[166:169], v[218:221], v[8:11]
	v_mfma_f32_16x16x32_bf16 v[60:63], v[162:165], v[194:197], v[60:63]
	v_mfma_f32_16x16x32_bf16 v[56:59], v[170:173], v[194:197], v[56:59]
	v_mfma_f32_16x16x32_bf16 v[44:47], v[162:165], v[206:209], v[44:47]
	v_mfma_f32_16x16x32_bf16 v[40:43], v[170:173], v[206:209], v[40:43]
	v_mfma_f32_16x16x32_bf16 v[28:31], v[162:165], v[214:217], v[28:31]
	v_mfma_f32_16x16x32_bf16 v[24:27], v[170:173], v[214:217], v[24:27]
	v_mfma_f32_16x16x32_bf16 v[12:15], v[162:165], v[222:225], v[12:15]
	v_mfma_f32_16x16x32_bf16 v[8:11], v[170:173], v[222:225], v[8:11]
	v_mfma_f32_16x16x32_bf16 v[52:55], v[174:177], v[190:193], v[52:55]
	v_mfma_f32_16x16x32_bf16 v[48:51], v[182:185], v[190:193], v[48:51]
	v_mfma_f32_16x16x32_bf16 v[36:39], v[174:177], v[202:205], v[36:39]
	v_mfma_f32_16x16x32_bf16 v[32:35], v[182:185], v[202:205], v[32:35]
	v_mfma_f32_16x16x32_bf16 v[20:23], v[174:177], v[210:213], v[20:23]
	v_mfma_f32_16x16x32_bf16 v[16:19], v[182:185], v[210:213], v[16:19]
	v_mfma_f32_16x16x32_bf16 v[4:7], v[174:177], v[218:221], v[4:7]
	v_mfma_f32_16x16x32_bf16 v[0:3], v[182:185], v[218:221], v[0:3]
	v_mfma_f32_16x16x32_bf16 v[52:55], v[178:181], v[194:197], v[52:55]
	v_mfma_f32_16x16x32_bf16 v[48:51], v[186:189], v[194:197], v[48:51]
	v_mfma_f32_16x16x32_bf16 v[36:39], v[178:181], v[206:209], v[36:39]
	v_mfma_f32_16x16x32_bf16 v[32:35], v[186:189], v[206:209], v[32:35]
	v_mfma_f32_16x16x32_bf16 v[20:23], v[178:181], v[214:217], v[20:23]
	v_mfma_f32_16x16x32_bf16 v[16:19], v[186:189], v[214:217], v[16:19]
	v_mfma_f32_16x16x32_bf16 v[4:7], v[178:181], v[222:225], v[4:7]
	v_mfma_f32_16x16x32_bf16 v[0:3], v[186:189], v[222:225], v[0:3]
	s_setprio 0
	s_barrier
	s_add_i32 vcc_hi, 0, 0x18000
	v_add_u32_e32 v136, vcc_hi, v156
	s_add_i32 s14, 0, 0x1c000
	ds_read_b128 v[152:155], v136
	ds_read_b128 v[162:165], v136 offset:1024
	ds_read_b128 v[166:169], v136 offset:2048
	ds_read_b128 v[170:173], v136 offset:3072
	v_add_u32_e32 v136, s14, v156
	ds_read_b128 v[174:177], v136
	ds_read_b128 v[178:181], v136 offset:1024
	ds_read_b128 v[182:185], v136 offset:2048
	ds_read_b128 v[186:189], v136 offset:3072
	s_add_u32 s12, s82, 0x40000
	s_addc_u32 s13, s83, 0
	s_mov_b32 m0, s77
	v_lshl_add_u64 v[234:235], s[12:13], 0, v[134:135]
	ds_read_b128 v[190:193], v161 offset:32768
	ds_read_b128 v[194:197], v161 offset:33792
	ds_read_b128 v[202:205], v161 offset:34816
	ds_read_b128 v[206:209], v161 offset:35840
	ds_read_b128 v[210:213], v161 offset:36864
	ds_read_b128 v[214:217], v161 offset:37888
	ds_read_b128 v[218:221], v161 offset:38912
	ds_read_b128 v[222:225], v161 offset:39936
	global_load_lds_dwordx4 v[234:235], off
	v_lshl_add_u64 v[234:235], s[12:13], 0, v[130:131]
	s_mov_b32 m0, s87
	s_nop 0
	global_load_lds_dwordx4 v[234:235], off
	s_waitcnt vmcnt(8)
	s_waitcnt lgkmcnt(0)
	s_barrier
	s_setprio 1
	s_waitcnt lgkmcnt(0)
	v_mfma_f32_16x16x32_bf16 v[124:127], v[152:155], v[190:193], v[124:127]
	v_mfma_f32_16x16x32_bf16 v[120:123], v[166:169], v[190:193], v[120:123]
	v_mfma_f32_16x16x32_bf16 v[108:111], v[152:155], v[202:205], v[108:111]
	v_mfma_f32_16x16x32_bf16 v[104:107], v[166:169], v[202:205], v[104:107]
	v_mfma_f32_16x16x32_bf16 v[92:95], v[152:155], v[210:213], v[92:95]
	v_mfma_f32_16x16x32_bf16 v[88:91], v[166:169], v[210:213], v[88:91]
	v_mfma_f32_16x16x32_bf16 v[76:79], v[152:155], v[218:221], v[76:79]
	v_mfma_f32_16x16x32_bf16 v[72:75], v[166:169], v[218:221], v[72:75]
	v_mfma_f32_16x16x32_bf16 v[124:127], v[162:165], v[194:197], v[124:127]
	v_mfma_f32_16x16x32_bf16 v[120:123], v[170:173], v[194:197], v[120:123]
	v_mfma_f32_16x16x32_bf16 v[108:111], v[162:165], v[206:209], v[108:111]
	v_mfma_f32_16x16x32_bf16 v[104:107], v[170:173], v[206:209], v[104:107]
	v_mfma_f32_16x16x32_bf16 v[92:95], v[162:165], v[214:217], v[92:95]
	v_mfma_f32_16x16x32_bf16 v[88:91], v[170:173], v[214:217], v[88:91]
	v_mfma_f32_16x16x32_bf16 v[76:79], v[162:165], v[222:225], v[76:79]
	v_mfma_f32_16x16x32_bf16 v[72:75], v[170:173], v[222:225], v[72:75]
	v_mfma_f32_16x16x32_bf16 v[116:119], v[174:177], v[190:193], v[116:119]
	v_mfma_f32_16x16x32_bf16 v[112:115], v[182:185], v[190:193], v[112:115]
	v_mfma_f32_16x16x32_bf16 v[100:103], v[174:177], v[202:205], v[100:103]
	v_mfma_f32_16x16x32_bf16 v[96:99], v[182:185], v[202:205], v[96:99]
	v_mfma_f32_16x16x32_bf16 v[84:87], v[174:177], v[210:213], v[84:87]
	v_mfma_f32_16x16x32_bf16 v[80:83], v[182:185], v[210:213], v[80:83]
	v_mfma_f32_16x16x32_bf16 v[68:71], v[174:177], v[218:221], v[68:71]
	v_mfma_f32_16x16x32_bf16 v[64:67], v[182:185], v[218:221], v[64:67]
	v_mfma_f32_16x16x32_bf16 v[116:119], v[178:181], v[194:197], v[116:119]
	v_mfma_f32_16x16x32_bf16 v[112:115], v[186:189], v[194:197], v[112:115]
	v_mfma_f32_16x16x32_bf16 v[100:103], v[178:181], v[206:209], v[100:103]
	v_mfma_f32_16x16x32_bf16 v[96:99], v[186:189], v[206:209], v[96:99]
	v_mfma_f32_16x16x32_bf16 v[84:87], v[178:181], v[214:217], v[84:87]
	v_mfma_f32_16x16x32_bf16 v[80:83], v[186:189], v[214:217], v[80:83]
	v_mfma_f32_16x16x32_bf16 v[68:71], v[178:181], v[222:225], v[68:71]
	v_mfma_f32_16x16x32_bf16 v[64:67], v[186:189], v[222:225], v[64:67]
	s_setprio 0
	s_barrier
	s_add_i32 s12, vcc_hi, s3
	v_lshl_add_u64 v[198:199], v[198:199], 0, s[90:91]
	s_mov_b32 m0, s12
	ds_read_b128 v[190:193], v161 offset:49152
	ds_read_b128 v[194:197], v161 offset:50176
	ds_read_b128 v[202:205], v161 offset:51200
	ds_read_b128 v[206:209], v161 offset:52224
	ds_read_b128 v[210:213], v161 offset:53248
	ds_read_b128 v[214:217], v161 offset:54272
	ds_read_b128 v[218:221], v161 offset:55296
	ds_read_b128 v[222:225], v161 offset:56320
	global_load_lds_dwordx4 v[198:199], off
	s_add_i32 m0, s12, 0x2000
	s_add_u32 s4, s4, 0x40080
	v_lshl_add_u64 v[198:199], v[226:227], 0, s[90:91]
	s_addc_u32 s5, s5, 0
	s_add_i32 s12, s14, s3
	global_load_lds_dwordx4 v[198:199], off
	v_lshl_add_u64 v[198:199], s[4:5], 0, v[132:133]
	s_mov_b32 m0, s12
	s_nop 0
	global_load_lds_dwordx4 v[198:199], off
	v_lshl_add_u64 v[198:199], s[4:5], 0, v[128:129]
	s_add_i32 m0, s12, 0x2000
	s_nop 0
	global_load_lds_dwordx4 v[198:199], off
	v_lshl_add_u64 v[198:199], v[228:229], 0, s[90:91]
	s_mov_b32 m0, s97
	s_nop 0
	global_load_lds_dwordx4 v[198:199], off
	v_lshl_add_u64 v[198:199], v[230:231], 0, s[90:91]
	s_mov_b32 m0, s99
	s_nop 0
	global_load_lds_dwordx4 v[198:199], off
	s_waitcnt vmcnt(8)
	s_waitcnt lgkmcnt(0)
	s_barrier
	s_setprio 1
	s_waitcnt lgkmcnt(0)
	v_mfma_f32_16x16x32_bf16 v[60:63], v[152:155], v[190:193], v[60:63]
	v_mfma_f32_16x16x32_bf16 v[56:59], v[166:169], v[190:193], v[56:59]
	v_mfma_f32_16x16x32_bf16 v[44:47], v[152:155], v[202:205], v[44:47]
	v_mfma_f32_16x16x32_bf16 v[40:43], v[166:169], v[202:205], v[40:43]
	v_mfma_f32_16x16x32_bf16 v[28:31], v[152:155], v[210:213], v[28:31]
	v_mfma_f32_16x16x32_bf16 v[24:27], v[166:169], v[210:213], v[24:27]
	v_mfma_f32_16x16x32_bf16 v[12:15], v[152:155], v[218:221], v[12:15]
	v_mfma_f32_16x16x32_bf16 v[8:11], v[166:169], v[218:221], v[8:11]
	v_mfma_f32_16x16x32_bf16 v[60:63], v[162:165], v[194:197], v[60:63]
	v_mfma_f32_16x16x32_bf16 v[56:59], v[170:173], v[194:197], v[56:59]
	v_mfma_f32_16x16x32_bf16 v[44:47], v[162:165], v[206:209], v[44:47]
	v_mfma_f32_16x16x32_bf16 v[40:43], v[170:173], v[206:209], v[40:43]
	v_mfma_f32_16x16x32_bf16 v[28:31], v[162:165], v[214:217], v[28:31]
	v_mfma_f32_16x16x32_bf16 v[24:27], v[170:173], v[214:217], v[24:27]
	v_mfma_f32_16x16x32_bf16 v[12:15], v[162:165], v[222:225], v[12:15]
	v_mfma_f32_16x16x32_bf16 v[8:11], v[170:173], v[222:225], v[8:11]
	v_mfma_f32_16x16x32_bf16 v[52:55], v[174:177], v[190:193], v[52:55]
	v_mfma_f32_16x16x32_bf16 v[48:51], v[182:185], v[190:193], v[48:51]
	v_mfma_f32_16x16x32_bf16 v[36:39], v[174:177], v[202:205], v[36:39]
	v_mfma_f32_16x16x32_bf16 v[32:35], v[182:185], v[202:205], v[32:35]
	v_mfma_f32_16x16x32_bf16 v[20:23], v[174:177], v[210:213], v[20:23]
	v_mfma_f32_16x16x32_bf16 v[16:19], v[182:185], v[210:213], v[16:19]
	v_mfma_f32_16x16x32_bf16 v[4:7], v[174:177], v[218:221], v[4:7]
	v_mfma_f32_16x16x32_bf16 v[0:3], v[182:185], v[218:221], v[0:3]
	v_mfma_f32_16x16x32_bf16 v[52:55], v[178:181], v[194:197], v[52:55]
	v_mfma_f32_16x16x32_bf16 v[48:51], v[186:189], v[194:197], v[48:51]
	v_mfma_f32_16x16x32_bf16 v[36:39], v[178:181], v[206:209], v[36:39]
	v_mfma_f32_16x16x32_bf16 v[32:35], v[186:189], v[206:209], v[32:35]
	v_mfma_f32_16x16x32_bf16 v[20:23], v[178:181], v[214:217], v[20:23]
	v_mfma_f32_16x16x32_bf16 v[16:19], v[186:189], v[214:217], v[16:19]
	v_mfma_f32_16x16x32_bf16 v[4:7], v[178:181], v[222:225], v[4:7]
	v_mfma_f32_16x16x32_bf16 v[0:3], v[186:189], v[222:225], v[0:3]
	s_setprio 0
	s_barrier
	s_add_i32 vcc_lo, vcc_lo, 2
	s_add_u32 s0, s0, 0x100
	s_addc_u32 s1, s1, 0
	s_add_u32 s53, s53, 0x100
	s_addc_u32 s79, s79, 0
	s_cmp_gt_u32 vcc_lo, 13
	s_cbranch_scc0 .LBB0_180
	s_and_b64 vcc, exec, s[92:93]
	s_cbranch_vccnz .LBB0_184
	s_cmp_gt_i32 s11, 3
	s_mov_b64 s[0:1], -1
	s_cbranch_scc1 .LBB0_185

.LBB0_306:
	ds_read_b128 v[112:115], v213
	ds_read_b128 v[116:119], v213 offset:1024
	ds_read_b128 v[136:139], v213 offset:2048
	ds_read_b128 v[140:143], v213 offset:3072
	ds_read_b128 v[144:147], v243
	ds_read_b128 v[148:151], v243 offset:1024
	ds_read_b128 v[152:155], v243 offset:2048
	ds_read_b128 v[156:159], v243 offset:3072
	s_add_u32 s17, s8, 0xfffc0080
	s_addc_u32 s26, s9, -1
	s_cmp_eq_u32 s16, 12
	s_cselect_b32 s73, s11, s26
	s_cselect_b32 s72, s87, s17
	s_cselect_b32 s41, s89, vcc_hi
	s_cselect_b32 s40, s95, vcc_lo
	v_lshl_add_u64 v[192:193], s[8:9], 0, v[220:221]
	s_add_i32 m0, s55, 0xc000
	ds_read_b128 v[160:163], v244
	ds_read_b128 v[164:167], v244 offset:1024
	ds_read_b128 v[168:171], v244 offset:2048
	ds_read_b128 v[172:175], v244 offset:3072
	ds_read_b128 v[176:179], v244 offset:4096
	ds_read_b128 v[180:183], v244 offset:5120
	ds_read_b128 v[184:187], v244 offset:6144
	ds_read_b128 v[188:191], v244 offset:7168
	global_load_lds_dwordx4 v[192:193], off
	v_lshl_add_u64 v[192:193], s[8:9], 0, v[222:223]
	s_add_i32 m0, s55, 0xe000
	s_nop 0
	global_load_lds_dwordx4 v[192:193], off
	s_waitcnt vmcnt(8)
	s_waitcnt lgkmcnt(0)
	s_barrier
	s_setprio 1
	s_waitcnt lgkmcnt(0)
	v_mfma_f32_16x16x32_bf16 v[132:135], v[112:115], v[160:163], v[132:135]
	v_mfma_f32_16x16x32_bf16 v[124:127], v[136:139], v[160:163], v[124:127]
	v_mfma_f32_16x16x32_bf16 v[108:111], v[112:115], v[168:171], v[108:111]
	v_mfma_f32_16x16x32_bf16 v[100:103], v[136:139], v[168:171], v[100:103]
	v_mfma_f32_16x16x32_bf16 v[92:95], v[112:115], v[176:179], v[92:95]
	v_mfma_f32_16x16x32_bf16 v[84:87], v[136:139], v[176:179], v[84:87]
	v_mfma_f32_16x16x32_bf16 v[76:79], v[112:115], v[184:187], v[76:79]
	v_mfma_f32_16x16x32_bf16 v[68:71], v[136:139], v[184:187], v[68:71]
	v_mfma_f32_16x16x32_bf16 v[132:135], v[116:119], v[164:167], v[132:135]
	v_mfma_f32_16x16x32_bf16 v[124:127], v[140:143], v[164:167], v[124:127]
	v_mfma_f32_16x16x32_bf16 v[108:111], v[116:119], v[172:175], v[108:111]
	v_mfma_f32_16x16x32_bf16 v[100:103], v[140:143], v[172:175], v[100:103]
	v_mfma_f32_16x16x32_bf16 v[92:95], v[116:119], v[180:183], v[92:95]
	v_mfma_f32_16x16x32_bf16 v[84:87], v[140:143], v[180:183], v[84:87]
	v_mfma_f32_16x16x32_bf16 v[76:79], v[116:119], v[188:191], v[76:79]
	v_mfma_f32_16x16x32_bf16 v[68:71], v[140:143], v[188:191], v[68:71]
	v_mfma_f32_16x16x32_bf16 v[128:131], v[144:147], v[160:163], v[128:131]
	v_mfma_f32_16x16x32_bf16 v[120:123], v[152:155], v[160:163], v[120:123]
	v_mfma_f32_16x16x32_bf16 v[104:107], v[144:147], v[168:171], v[104:107]
	v_mfma_f32_16x16x32_bf16 v[96:99], v[152:155], v[168:171], v[96:99]
	v_mfma_f32_16x16x32_bf16 v[88:91], v[144:147], v[176:179], v[88:91]
	v_mfma_f32_16x16x32_bf16 v[80:83], v[152:155], v[176:179], v[80:83]
	v_mfma_f32_16x16x32_bf16 v[72:75], v[144:147], v[184:187], v[72:75]
	v_mfma_f32_16x16x32_bf16 v[64:67], v[152:155], v[184:187], v[64:67]
	v_mfma_f32_16x16x32_bf16 v[128:131], v[148:151], v[164:167], v[128:131]
	v_mfma_f32_16x16x32_bf16 v[120:123], v[156:159], v[164:167], v[120:123]
	v_mfma_f32_16x16x32_bf16 v[104:107], v[148:151], v[172:175], v[104:107]
	v_mfma_f32_16x16x32_bf16 v[96:99], v[156:159], v[172:175], v[96:99]
	v_mfma_f32_16x16x32_bf16 v[88:91], v[148:151], v[180:183], v[88:91]
	v_mfma_f32_16x16x32_bf16 v[80:83], v[156:159], v[180:183], v[80:83]
	v_mfma_f32_16x16x32_bf16 v[72:75], v[148:151], v[188:191], v[72:75]
	v_mfma_f32_16x16x32_bf16 v[64:67], v[156:159], v[188:191], v[64:67]
	s_setprio 0
	s_barrier
	s_add_i32 s17, s3, s53
	v_lshl_add_u64 v[192:193], s[40:41], 0, v[204:205]
	s_mov_b32 m0, s17
	ds_read_b128 v[160:163], v244 offset:16384
	ds_read_b128 v[164:167], v244 offset:17408
	ds_read_b128 v[168:171], v244 offset:18432
	ds_read_b128 v[172:175], v244 offset:19456
	ds_read_b128 v[176:179], v244 offset:20480
	ds_read_b128 v[180:183], v244 offset:21504
	ds_read_b128 v[184:187], v244 offset:22528
	ds_read_b128 v[188:191], v244 offset:23552
	global_load_lds_dwordx4 v[192:193], off
	s_add_i32 m0, s17, 0x2000
	s_add_u32 s26, s40, 0x40000
	v_lshl_add_u64 v[194:195], s[40:41], 0, v[208:209]
	s_addc_u32 s27, s41, 0
	s_add_i32 s17, s33, s53
	global_load_lds_dwordx4 v[194:195], off
	v_lshl_add_u64 v[196:197], s[26:27], 0, v[204:205]
	s_mov_b32 m0, s17
	v_lshl_add_u64 v[198:199], s[72:73], 0, v[206:207]
	global_load_lds_dwordx4 v[196:197], off
	v_lshl_add_u64 v[196:197], s[26:27], 0, v[208:209]
	s_add_i32 m0, s17, 0x2000
	s_nop 0
	global_load_lds_dwordx4 v[196:197], off
	v_lshl_add_u64 v[196:197], s[72:73], 0, v[202:203]
	s_mov_b32 m0, s55
	s_nop 0
	global_load_lds_dwordx4 v[196:197], off
	s_mov_b32 m0, s63
	s_nop 0
	global_load_lds_dwordx4 v[198:199], off
	s_waitcnt vmcnt(8)
	s_waitcnt lgkmcnt(0)
	s_barrier
	s_setprio 1
	s_waitcnt lgkmcnt(0)
	v_mfma_f32_16x16x32_bf16 v[60:63], v[112:115], v[160:163], v[60:63]
	v_mfma_f32_16x16x32_bf16 v[52:55], v[136:139], v[160:163], v[52:55]
	v_mfma_f32_16x16x32_bf16 v[44:47], v[112:115], v[168:171], v[44:47]
	v_mfma_f32_16x16x32_bf16 v[36:39], v[136:139], v[168:171], v[36:39]
	v_mfma_f32_16x16x32_bf16 v[28:31], v[112:115], v[176:179], v[28:31]
	v_mfma_f32_16x16x32_bf16 v[20:23], v[136:139], v[176:179], v[20:23]
	v_mfma_f32_16x16x32_bf16 v[12:15], v[112:115], v[184:187], v[12:15]
	v_mfma_f32_16x16x32_bf16 v[4:7], v[136:139], v[184:187], v[4:7]
	v_mfma_f32_16x16x32_bf16 v[60:63], v[116:119], v[164:167], v[60:63]
	v_mfma_f32_16x16x32_bf16 v[52:55], v[140:143], v[164:167], v[52:55]
	v_mfma_f32_16x16x32_bf16 v[44:47], v[116:119], v[172:175], v[44:47]
	v_mfma_f32_16x16x32_bf16 v[36:39], v[140:143], v[172:175], v[36:39]
	v_mfma_f32_16x16x32_bf16 v[28:31], v[116:119], v[180:183], v[28:31]
	v_mfma_f32_16x16x32_bf16 v[20:23], v[140:143], v[180:183], v[20:23]
	v_mfma_f32_16x16x32_bf16 v[12:15], v[116:119], v[188:191], v[12:15]
	v_mfma_f32_16x16x32_bf16 v[4:7], v[140:143], v[188:191], v[4:7]
	v_mfma_f32_16x16x32_bf16 v[56:59], v[144:147], v[160:163], v[56:59]
	v_mfma_f32_16x16x32_bf16 v[48:51], v[152:155], v[160:163], v[48:51]
	v_mfma_f32_16x16x32_bf16 v[40:43], v[144:147], v[168:171], v[40:43]
	v_mfma_f32_16x16x32_bf16 v[32:35], v[152:155], v[168:171], v[32:35]
	v_mfma_f32_16x16x32_bf16 v[24:27], v[144:147], v[176:179], v[24:27]
	v_mfma_f32_16x16x32_bf16 v[16:19], v[152:155], v[176:179], v[16:19]
	v_mfma_f32_16x16x32_bf16 v[8:11], v[144:147], v[184:187], v[8:11]
	v_mfma_f32_16x16x32_bf16 v[0:3], v[152:155], v[184:187], v[0:3]
	v_mfma_f32_16x16x32_bf16 v[56:59], v[148:151], v[164:167], v[56:59]
	v_mfma_f32_16x16x32_bf16 v[48:51], v[156:159], v[164:167], v[48:51]
	v_mfma_f32_16x16x32_bf16 v[40:43], v[148:151], v[172:175], v[40:43]
	v_mfma_f32_16x16x32_bf16 v[32:35], v[156:159], v[172:175], v[32:35]
	v_mfma_f32_16x16x32_bf16 v[24:27], v[148:151], v[180:183], v[24:27]
	v_mfma_f32_16x16x32_bf16 v[16:19], v[156:159], v[180:183], v[16:19]
	v_mfma_f32_16x16x32_bf16 v[8:11], v[148:151], v[188:191], v[8:11]
	v_mfma_f32_16x16x32_bf16 v[0:3], v[156:159], v[188:191], v[0:3]
	s_setprio 0
	s_barrier
	s_add_i32 s17, 0, 0x18000
	s_add_i32 s28, 0, 0x1c000
	v_add_u32_e32 v140, s17, v235
	v_add_u32_e32 v156, s28, v235
	ds_read_b128 v[112:115], v140
	ds_read_b128 v[116:119], v140 offset:1024
	ds_read_b128 v[136:139], v140 offset:2048
	ds_read_b128 v[140:143], v140 offset:3072
	ds_read_b128 v[144:147], v156
	ds_read_b128 v[148:151], v156 offset:1024
	ds_read_b128 v[152:155], v156 offset:2048
	ds_read_b128 v[156:159], v156 offset:3072
	s_add_u32 s26, s72, 0x40000
	s_addc_u32 s27, s73, 0
	s_mov_b32 m0, s74
	v_lshl_add_u64 v[228:229], s[26:27], 0, v[202:203]
	ds_read_b128 v[160:163], v244 offset:32768
	ds_read_b128 v[164:167], v244 offset:33792
	ds_read_b128 v[168:171], v244 offset:34816
	ds_read_b128 v[172:175], v244 offset:35840
	ds_read_b128 v[176:179], v244 offset:36864
	ds_read_b128 v[180:183], v244 offset:37888
	ds_read_b128 v[184:187], v244 offset:38912
	ds_read_b128 v[188:191], v244 offset:39936
	global_load_lds_dwordx4 v[228:229], off
	v_lshl_add_u64 v[228:229], s[26:27], 0, v[206:207]
	s_mov_b32 m0, s76
	s_nop 0
	global_load_lds_dwordx4 v[228:229], off
	s_waitcnt vmcnt(8)
	s_waitcnt lgkmcnt(0)
	s_barrier
	s_setprio 1
	s_waitcnt lgkmcnt(0)
	v_mfma_f32_16x16x32_bf16 v[132:135], v[112:115], v[160:163], v[132:135]
	v_mfma_f32_16x16x32_bf16 v[124:127], v[136:139], v[160:163], v[124:127]
	v_mfma_f32_16x16x32_bf16 v[108:111], v[112:115], v[168:171], v[108:111]
	v_mfma_f32_16x16x32_bf16 v[100:103], v[136:139], v[168:171], v[100:103]
	v_mfma_f32_16x16x32_bf16 v[92:95], v[112:115], v[176:179], v[92:95]
	v_mfma_f32_16x16x32_bf16 v[84:87], v[136:139], v[176:179], v[84:87]
	v_mfma_f32_16x16x32_bf16 v[76:79], v[112:115], v[184:187], v[76:79]
	v_mfma_f32_16x16x32_bf16 v[68:71], v[136:139], v[184:187], v[68:71]
	v_mfma_f32_16x16x32_bf16 v[132:135], v[116:119], v[164:167], v[132:135]
	v_mfma_f32_16x16x32_bf16 v[124:127], v[140:143], v[164:167], v[124:127]
	v_mfma_f32_16x16x32_bf16 v[108:111], v[116:119], v[172:175], v[108:111]
	v_mfma_f32_16x16x32_bf16 v[100:103], v[140:143], v[172:175], v[100:103]
	v_mfma_f32_16x16x32_bf16 v[92:95], v[116:119], v[180:183], v[92:95]
	v_mfma_f32_16x16x32_bf16 v[84:87], v[140:143], v[180:183], v[84:87]
	v_mfma_f32_16x16x32_bf16 v[76:79], v[116:119], v[188:191], v[76:79]
	v_mfma_f32_16x16x32_bf16 v[68:71], v[140:143], v[188:191], v[68:71]
	v_mfma_f32_16x16x32_bf16 v[128:131], v[144:147], v[160:163], v[128:131]
	v_mfma_f32_16x16x32_bf16 v[120:123], v[152:155], v[160:163], v[120:123]
	v_mfma_f32_16x16x32_bf16 v[104:107], v[144:147], v[168:171], v[104:107]
	v_mfma_f32_16x16x32_bf16 v[96:99], v[152:155], v[168:171], v[96:99]
	v_mfma_f32_16x16x32_bf16 v[88:91], v[144:147], v[176:179], v[88:91]
	v_mfma_f32_16x16x32_bf16 v[80:83], v[152:155], v[176:179], v[80:83]
	v_mfma_f32_16x16x32_bf16 v[72:75], v[144:147], v[184:187], v[72:75]
	v_mfma_f32_16x16x32_bf16 v[64:67], v[152:155], v[184:187], v[64:67]
	v_mfma_f32_16x16x32_bf16 v[128:131], v[148:151], v[164:167], v[128:131]
	v_mfma_f32_16x16x32_bf16 v[120:123], v[156:159], v[164:167], v[120:123]
	v_mfma_f32_16x16x32_bf16 v[104:107], v[148:151], v[172:175], v[104:107]
	v_mfma_f32_16x16x32_bf16 v[96:99], v[156:159], v[172:175], v[96:99]
	v_mfma_f32_16x16x32_bf16 v[88:91], v[148:151], v[180:183], v[88:91]
	v_mfma_f32_16x16x32_bf16 v[80:83], v[156:159], v[180:183], v[80:83]
	v_mfma_f32_16x16x32_bf16 v[72:75], v[148:151], v[188:191], v[72:75]
	v_mfma_f32_16x16x32_bf16 v[64:67], v[156:159], v[188:191], v[64:67]
	s_setprio 0
	s_barrier
	s_add_i32 s17, s17, s53
	v_lshl_add_u64 v[192:193], v[192:193], 0, s[20:21]
	s_mov_b32 m0, s17
	ds_read_b128 v[160:163], v244 offset:49152
	ds_read_b128 v[164:167], v244 offset:50176
	ds_read_b128 v[168:171], v244 offset:51200
	ds_read_b128 v[172:175], v244 offset:52224
	ds_read_b128 v[176:179], v244 offset:53248
	ds_read_b128 v[180:183], v244 offset:54272
	ds_read_b128 v[184:187], v244 offset:55296
	ds_read_b128 v[188:191], v244 offset:56320
	global_load_lds_dwordx4 v[192:193], off
	s_add_i32 m0, s17, 0x2000
	s_add_u32 s26, s40, 0x40080
	v_lshl_add_u64 v[192:193], v[194:195], 0, s[20:21]
	s_addc_u32 s27, s41, 0
	s_add_i32 s17, s28, s53
	global_load_lds_dwordx4 v[192:193], off
	v_lshl_add_u64 v[192:193], s[26:27], 0, v[204:205]
	s_mov_b32 m0, s17
	s_nop 0
	global_load_lds_dwordx4 v[192:193], off
	v_lshl_add_u64 v[192:193], s[26:27], 0, v[208:209]
	s_add_i32 m0, s17, 0x2000
	s_nop 0
	global_load_lds_dwordx4 v[192:193], off
	v_lshl_add_u64 v[192:193], v[196:197], 0, s[20:21]
	s_mov_b32 m0, s78
	s_nop 0
	global_load_lds_dwordx4 v[192:193], off
	v_lshl_add_u64 v[192:193], v[198:199], 0, s[20:21]
	s_mov_b32 m0, s79
	s_nop 0
	global_load_lds_dwordx4 v[192:193], off
	s_waitcnt vmcnt(8)
	s_waitcnt lgkmcnt(0)
	s_barrier
	s_setprio 1
	s_waitcnt lgkmcnt(0)
	v_mfma_f32_16x16x32_bf16 v[60:63], v[112:115], v[160:163], v[60:63]
	v_mfma_f32_16x16x32_bf16 v[52:55], v[136:139], v[160:163], v[52:55]
	v_mfma_f32_16x16x32_bf16 v[44:47], v[112:115], v[168:171], v[44:47]
	v_mfma_f32_16x16x32_bf16 v[36:39], v[136:139], v[168:171], v[36:39]
	v_mfma_f32_16x16x32_bf16 v[28:31], v[112:115], v[176:179], v[28:31]
	v_mfma_f32_16x16x32_bf16 v[20:23], v[136:139], v[176:179], v[20:23]
	v_mfma_f32_16x16x32_bf16 v[12:15], v[112:115], v[184:187], v[12:15]
	v_mfma_f32_16x16x32_bf16 v[4:7], v[136:139], v[184:187], v[4:7]
	v_mfma_f32_16x16x32_bf16 v[60:63], v[116:119], v[164:167], v[60:63]
	v_mfma_f32_16x16x32_bf16 v[52:55], v[140:143], v[164:167], v[52:55]
	v_mfma_f32_16x16x32_bf16 v[44:47], v[116:119], v[172:175], v[44:47]
	v_mfma_f32_16x16x32_bf16 v[36:39], v[140:143], v[172:175], v[36:39]
	v_mfma_f32_16x16x32_bf16 v[28:31], v[116:119], v[180:183], v[28:31]
	v_mfma_f32_16x16x32_bf16 v[20:23], v[140:143], v[180:183], v[20:23]
	v_mfma_f32_16x16x32_bf16 v[12:15], v[116:119], v[188:191], v[12:15]
	v_mfma_f32_16x16x32_bf16 v[4:7], v[140:143], v[188:191], v[4:7]
	v_mfma_f32_16x16x32_bf16 v[56:59], v[144:147], v[160:163], v[56:59]
	v_mfma_f32_16x16x32_bf16 v[48:51], v[152:155], v[160:163], v[48:51]
	v_mfma_f32_16x16x32_bf16 v[40:43], v[144:147], v[168:171], v[40:43]
	v_mfma_f32_16x16x32_bf16 v[32:35], v[152:155], v[168:171], v[32:35]
	v_mfma_f32_16x16x32_bf16 v[24:27], v[144:147], v[176:179], v[24:27]
	v_mfma_f32_16x16x32_bf16 v[16:19], v[152:155], v[176:179], v[16:19]
	v_mfma_f32_16x16x32_bf16 v[8:11], v[144:147], v[184:187], v[8:11]
	v_mfma_f32_16x16x32_bf16 v[0:3], v[152:155], v[184:187], v[0:3]
	v_mfma_f32_16x16x32_bf16 v[56:59], v[148:151], v[164:167], v[56:59]
	v_mfma_f32_16x16x32_bf16 v[48:51], v[156:159], v[164:167], v[48:51]
	v_mfma_f32_16x16x32_bf16 v[40:43], v[148:151], v[172:175], v[40:43]
	v_mfma_f32_16x16x32_bf16 v[32:35], v[156:159], v[172:175], v[32:35]
	v_mfma_f32_16x16x32_bf16 v[24:27], v[148:151], v[180:183], v[24:27]
	v_mfma_f32_16x16x32_bf16 v[16:19], v[156:159], v[180:183], v[16:19]
	v_mfma_f32_16x16x32_bf16 v[8:11], v[148:151], v[188:191], v[8:11]
	v_mfma_f32_16x16x32_bf16 v[0:3], v[156:159], v[188:191], v[0:3]
	s_setprio 0
	s_barrier
	s_add_i32 s16, s16, 2
	s_add_u32 s8, s8, 0x100
	s_addc_u32 s9, s9, 0
	s_add_u32 vcc_lo, vcc_lo, 0x100
	s_addc_u32 vcc_hi, vcc_hi, 0
	s_cmp_gt_u32 s16, 13
	s_cbranch_scc0 .LBB0_306
	s_and_b64 vcc, exec, s[22:23]
	s_cbranch_vccnz .LBB0_311
	s_lshl_b32 s87, s10, 7
	s_cmp_gt_i32 s10, 7
	s_mov_b64 s[8:9], -1
	s_cbranch_scc1 .LBB0_312

.LBB0_455:
	ds_read_b128 v[140:143], v147
	ds_read_b128 v[152:155], v147 offset:1024
	ds_read_b128 v[156:159], v147 offset:2048
	ds_read_b128 v[160:163], v147 offset:3072
	ds_read_b128 v[164:167], v148
	ds_read_b128 v[168:171], v148 offset:1024
	ds_read_b128 v[172:175], v148 offset:2048
	ds_read_b128 v[176:179], v148 offset:3072
	s_add_u32 s36, s34, 0xfff80080
	s_addc_u32 s37, s35, -1
	s_cmp_eq_u32 s58, 28
	s_cselect_b32 s39, s21, s37
	s_cselect_b32 s38, s23, s36
	s_cselect_b32 s37, s29, s57
	s_cselect_b32 s36, s55, s56
	v_lshl_add_u64 v[214:215], s[34:35], 0, v[132:133]
	s_add_i32 m0, s31, 0xc000
	ds_read_b128 v[180:183], v149
	ds_read_b128 v[184:187], v149 offset:1024
	ds_read_b128 v[188:191], v149 offset:2048
	ds_read_b128 v[192:195], v149 offset:3072
	ds_read_b128 v[196:199], v149 offset:4096
	ds_read_b128 v[202:205], v149 offset:5120
	ds_read_b128 v[206:209], v149 offset:6144
	ds_read_b128 v[210:213], v149 offset:7168
	global_load_lds_dwordx4 v[214:215], off
	v_lshl_add_u64 v[214:215], s[34:35], 0, v[134:135]
	s_add_i32 m0, s31, 0xe000
	s_nop 0
	global_load_lds_dwordx4 v[214:215], off
	s_waitcnt vmcnt(8)
	s_waitcnt lgkmcnt(0)
	s_barrier
	s_setprio 1
	s_waitcnt lgkmcnt(0)
	v_mfma_f32_16x16x32_bf16 v[124:127], v[140:143], v[180:183], v[124:127]
	v_mfma_f32_16x16x32_bf16 v[120:123], v[156:159], v[180:183], v[120:123]
	v_mfma_f32_16x16x32_bf16 v[108:111], v[140:143], v[188:191], v[108:111]
	v_mfma_f32_16x16x32_bf16 v[104:107], v[156:159], v[188:191], v[104:107]
	v_mfma_f32_16x16x32_bf16 v[92:95], v[140:143], v[196:199], v[92:95]
	v_mfma_f32_16x16x32_bf16 v[88:91], v[156:159], v[196:199], v[88:91]
	v_mfma_f32_16x16x32_bf16 v[76:79], v[140:143], v[206:209], v[76:79]
	v_mfma_f32_16x16x32_bf16 v[72:75], v[156:159], v[206:209], v[72:75]
	v_mfma_f32_16x16x32_bf16 v[124:127], v[152:155], v[184:187], v[124:127]
	v_mfma_f32_16x16x32_bf16 v[120:123], v[160:163], v[184:187], v[120:123]
	v_mfma_f32_16x16x32_bf16 v[108:111], v[152:155], v[192:195], v[108:111]
	v_mfma_f32_16x16x32_bf16 v[104:107], v[160:163], v[192:195], v[104:107]
	v_mfma_f32_16x16x32_bf16 v[92:95], v[152:155], v[202:205], v[92:95]
	v_mfma_f32_16x16x32_bf16 v[88:91], v[160:163], v[202:205], v[88:91]
	v_mfma_f32_16x16x32_bf16 v[76:79], v[152:155], v[210:213], v[76:79]
	v_mfma_f32_16x16x32_bf16 v[72:75], v[160:163], v[210:213], v[72:75]
	v_mfma_f32_16x16x32_bf16 v[116:119], v[164:167], v[180:183], v[116:119]
	v_mfma_f32_16x16x32_bf16 v[112:115], v[172:175], v[180:183], v[112:115]
	v_mfma_f32_16x16x32_bf16 v[100:103], v[164:167], v[188:191], v[100:103]
	v_mfma_f32_16x16x32_bf16 v[96:99], v[172:175], v[188:191], v[96:99]
	v_mfma_f32_16x16x32_bf16 v[84:87], v[164:167], v[196:199], v[84:87]
	v_mfma_f32_16x16x32_bf16 v[80:83], v[172:175], v[196:199], v[80:83]
	v_mfma_f32_16x16x32_bf16 v[68:71], v[164:167], v[206:209], v[68:71]
	v_mfma_f32_16x16x32_bf16 v[64:67], v[172:175], v[206:209], v[64:67]
	v_mfma_f32_16x16x32_bf16 v[116:119], v[168:171], v[184:187], v[116:119]
	v_mfma_f32_16x16x32_bf16 v[112:115], v[176:179], v[184:187], v[112:115]
	v_mfma_f32_16x16x32_bf16 v[100:103], v[168:171], v[192:195], v[100:103]
	v_mfma_f32_16x16x32_bf16 v[96:99], v[176:179], v[192:195], v[96:99]
	v_mfma_f32_16x16x32_bf16 v[84:87], v[168:171], v[202:205], v[84:87]
	v_mfma_f32_16x16x32_bf16 v[80:83], v[176:179], v[202:205], v[80:83]
	v_mfma_f32_16x16x32_bf16 v[68:71], v[168:171], v[210:213], v[68:71]
	v_mfma_f32_16x16x32_bf16 v[64:67], v[176:179], v[210:213], v[64:67]
	s_setprio 0
	s_barrier
	s_add_i32 s59, s53, s3
	v_lshl_add_u64 v[214:215], s[36:37], 0, v[128:129]
	s_mov_b32 m0, s59
	ds_read_b128 v[180:183], v149 offset:16384
	ds_read_b128 v[184:187], v149 offset:17408
	ds_read_b128 v[188:191], v149 offset:18432
	ds_read_b128 v[192:195], v149 offset:19456
	ds_read_b128 v[196:199], v149 offset:20480
	ds_read_b128 v[202:205], v149 offset:21504
	ds_read_b128 v[206:209], v149 offset:22528
	ds_read_b128 v[210:213], v149 offset:23552
	global_load_lds_dwordx4 v[214:215], off
	s_add_i32 m0, s59, 0x2000
	s_add_u32 s60, s36, 0x80000
	v_lshl_add_u64 v[216:217], s[36:37], 0, v[130:131]
	s_addc_u32 s61, s37, 0
	s_add_i32 s59, s54, s3
	global_load_lds_dwordx4 v[216:217], off
	v_lshl_add_u64 v[218:219], s[60:61], 0, v[128:129]
	s_mov_b32 m0, s59
	v_lshl_add_u64 v[220:221], s[38:39], 0, v[130:131]
	global_load_lds_dwordx4 v[218:219], off
	v_lshl_add_u64 v[218:219], s[60:61], 0, v[130:131]
	s_add_i32 m0, s59, 0x2000
	s_nop 0
	global_load_lds_dwordx4 v[218:219], off
	v_lshl_add_u64 v[218:219], s[38:39], 0, v[128:129]
	s_mov_b32 m0, s31
	s_nop 0
	global_load_lds_dwordx4 v[218:219], off
	s_mov_b32 m0, s33
	s_nop 0
	global_load_lds_dwordx4 v[220:221], off
	s_waitcnt vmcnt(8)
	s_waitcnt lgkmcnt(0)
	s_barrier
	s_setprio 1
	s_waitcnt lgkmcnt(0)
	v_mfma_f32_16x16x32_bf16 v[60:63], v[140:143], v[180:183], v[60:63]
	v_mfma_f32_16x16x32_bf16 v[56:59], v[156:159], v[180:183], v[56:59]
	v_mfma_f32_16x16x32_bf16 v[44:47], v[140:143], v[188:191], v[44:47]
	v_mfma_f32_16x16x32_bf16 v[40:43], v[156:159], v[188:191], v[40:43]
	v_mfma_f32_16x16x32_bf16 v[28:31], v[140:143], v[196:199], v[28:31]
	v_mfma_f32_16x16x32_bf16 v[24:27], v[156:159], v[196:199], v[24:27]
	v_mfma_f32_16x16x32_bf16 v[12:15], v[140:143], v[206:209], v[12:15]
	v_mfma_f32_16x16x32_bf16 v[8:11], v[156:159], v[206:209], v[8:11]
	v_mfma_f32_16x16x32_bf16 v[60:63], v[152:155], v[184:187], v[60:63]
	v_mfma_f32_16x16x32_bf16 v[56:59], v[160:163], v[184:187], v[56:59]
	v_mfma_f32_16x16x32_bf16 v[44:47], v[152:155], v[192:195], v[44:47]
	v_mfma_f32_16x16x32_bf16 v[40:43], v[160:163], v[192:195], v[40:43]
	v_mfma_f32_16x16x32_bf16 v[28:31], v[152:155], v[202:205], v[28:31]
	v_mfma_f32_16x16x32_bf16 v[24:27], v[160:163], v[202:205], v[24:27]
	v_mfma_f32_16x16x32_bf16 v[12:15], v[152:155], v[210:213], v[12:15]
	v_mfma_f32_16x16x32_bf16 v[8:11], v[160:163], v[210:213], v[8:11]
	v_mfma_f32_16x16x32_bf16 v[52:55], v[164:167], v[180:183], v[52:55]
	v_mfma_f32_16x16x32_bf16 v[48:51], v[172:175], v[180:183], v[48:51]
	v_mfma_f32_16x16x32_bf16 v[36:39], v[164:167], v[188:191], v[36:39]
	v_mfma_f32_16x16x32_bf16 v[32:35], v[172:175], v[188:191], v[32:35]
	v_mfma_f32_16x16x32_bf16 v[20:23], v[164:167], v[196:199], v[20:23]
	v_mfma_f32_16x16x32_bf16 v[16:19], v[172:175], v[196:199], v[16:19]
	v_mfma_f32_16x16x32_bf16 v[4:7], v[164:167], v[206:209], v[4:7]
	v_mfma_f32_16x16x32_bf16 v[0:3], v[172:175], v[206:209], v[0:3]
	v_mfma_f32_16x16x32_bf16 v[52:55], v[168:171], v[184:187], v[52:55]
	v_mfma_f32_16x16x32_bf16 v[48:51], v[176:179], v[184:187], v[48:51]
	v_mfma_f32_16x16x32_bf16 v[36:39], v[168:171], v[192:195], v[36:39]
	v_mfma_f32_16x16x32_bf16 v[32:35], v[176:179], v[192:195], v[32:35]
	v_mfma_f32_16x16x32_bf16 v[20:23], v[168:171], v[202:205], v[20:23]
	v_mfma_f32_16x16x32_bf16 v[16:19], v[176:179], v[202:205], v[16:19]
	v_mfma_f32_16x16x32_bf16 v[4:7], v[168:171], v[210:213], v[4:7]
	v_mfma_f32_16x16x32_bf16 v[0:3], v[176:179], v[210:213], v[0:3]
	s_setprio 0
	s_barrier
	s_add_i32 s59, 0, 0x18000
	v_add_u32_e32 v151, s59, v145
	s_add_i32 s60, 0, 0x1c000
	ds_read_b128 v[140:143], v151
	ds_read_b128 v[152:155], v151 offset:1024
	ds_read_b128 v[156:159], v151 offset:2048
	ds_read_b128 v[160:163], v151 offset:3072
	v_add_u32_e32 v151, s60, v145
	ds_read_b128 v[164:167], v151
	ds_read_b128 v[168:171], v151 offset:1024
	ds_read_b128 v[172:175], v151 offset:2048
	ds_read_b128 v[176:179], v151 offset:3072
	s_add_u32 s38, s38, 0x80000
	s_addc_u32 s39, s39, 0
	s_mov_b32 m0, s40
	v_lshl_add_u64 v[222:223], s[38:39], 0, v[128:129]
	ds_read_b128 v[180:183], v149 offset:32768
	ds_read_b128 v[184:187], v149 offset:33792
	ds_read_b128 v[188:191], v149 offset:34816
	ds_read_b128 v[192:195], v149 offset:35840
	ds_read_b128 v[196:199], v149 offset:36864
	ds_read_b128 v[202:205], v149 offset:37888
	ds_read_b128 v[206:209], v149 offset:38912
	ds_read_b128 v[210:213], v149 offset:39936
	global_load_lds_dwordx4 v[222:223], off
	v_lshl_add_u64 v[222:223], s[38:39], 0, v[130:131]
	s_mov_b32 m0, s41
	s_nop 0
	global_load_lds_dwordx4 v[222:223], off
	s_waitcnt vmcnt(8)
	s_waitcnt lgkmcnt(0)
	s_barrier
	s_setprio 1
	s_waitcnt lgkmcnt(0)
	v_mfma_f32_16x16x32_bf16 v[124:127], v[140:143], v[180:183], v[124:127]
	v_mfma_f32_16x16x32_bf16 v[120:123], v[156:159], v[180:183], v[120:123]
	v_mfma_f32_16x16x32_bf16 v[108:111], v[140:143], v[188:191], v[108:111]
	v_mfma_f32_16x16x32_bf16 v[104:107], v[156:159], v[188:191], v[104:107]
	v_mfma_f32_16x16x32_bf16 v[92:95], v[140:143], v[196:199], v[92:95]
	v_mfma_f32_16x16x32_bf16 v[88:91], v[156:159], v[196:199], v[88:91]
	v_mfma_f32_16x16x32_bf16 v[76:79], v[140:143], v[206:209], v[76:79]
	v_mfma_f32_16x16x32_bf16 v[72:75], v[156:159], v[206:209], v[72:75]
	v_mfma_f32_16x16x32_bf16 v[124:127], v[152:155], v[184:187], v[124:127]
	v_mfma_f32_16x16x32_bf16 v[120:123], v[160:163], v[184:187], v[120:123]
	v_mfma_f32_16x16x32_bf16 v[108:111], v[152:155], v[192:195], v[108:111]
	v_mfma_f32_16x16x32_bf16 v[104:107], v[160:163], v[192:195], v[104:107]
	v_mfma_f32_16x16x32_bf16 v[92:95], v[152:155], v[202:205], v[92:95]
	v_mfma_f32_16x16x32_bf16 v[88:91], v[160:163], v[202:205], v[88:91]
	v_mfma_f32_16x16x32_bf16 v[76:79], v[152:155], v[210:213], v[76:79]
	v_mfma_f32_16x16x32_bf16 v[72:75], v[160:163], v[210:213], v[72:75]
	v_mfma_f32_16x16x32_bf16 v[116:119], v[164:167], v[180:183], v[116:119]
	v_mfma_f32_16x16x32_bf16 v[112:115], v[172:175], v[180:183], v[112:115]
	v_mfma_f32_16x16x32_bf16 v[100:103], v[164:167], v[188:191], v[100:103]
	v_mfma_f32_16x16x32_bf16 v[96:99], v[172:175], v[188:191], v[96:99]
	v_mfma_f32_16x16x32_bf16 v[84:87], v[164:167], v[196:199], v[84:87]
	v_mfma_f32_16x16x32_bf16 v[80:83], v[172:175], v[196:199], v[80:83]
	v_mfma_f32_16x16x32_bf16 v[68:71], v[164:167], v[206:209], v[68:71]
	v_mfma_f32_16x16x32_bf16 v[64:67], v[172:175], v[206:209], v[64:67]
	v_mfma_f32_16x16x32_bf16 v[116:119], v[168:171], v[184:187], v[116:119]
	v_mfma_f32_16x16x32_bf16 v[112:115], v[176:179], v[184:187], v[112:115]
	v_mfma_f32_16x16x32_bf16 v[100:103], v[168:171], v[192:195], v[100:103]
	v_mfma_f32_16x16x32_bf16 v[96:99], v[176:179], v[192:195], v[96:99]
	v_mfma_f32_16x16x32_bf16 v[84:87], v[168:171], v[202:205], v[84:87]
	v_mfma_f32_16x16x32_bf16 v[80:83], v[176:179], v[202:205], v[80:83]
	v_mfma_f32_16x16x32_bf16 v[68:71], v[168:171], v[210:213], v[68:71]
	v_mfma_f32_16x16x32_bf16 v[64:67], v[176:179], v[210:213], v[64:67]
	s_setprio 0
	s_barrier
	s_add_i32 s38, s59, s3
	v_lshl_add_u64 v[214:215], v[214:215], 0, s[16:17]
	s_mov_b32 m0, s38
	ds_read_b128 v[180:183], v149 offset:49152
	ds_read_b128 v[184:187], v149 offset:50176
	ds_read_b128 v[188:191], v149 offset:51200
	ds_read_b128 v[192:195], v149 offset:52224
	ds_read_b128 v[196:199], v149 offset:53248
	ds_read_b128 v[202:205], v149 offset:54272
	ds_read_b128 v[206:209], v149 offset:55296
	ds_read_b128 v[210:213], v149 offset:56320
	global_load_lds_dwordx4 v[214:215], off
	s_add_i32 m0, s38, 0x2000
	s_add_u32 s36, s36, 0x80080
	v_lshl_add_u64 v[214:215], v[216:217], 0, s[16:17]
	s_addc_u32 s37, s37, 0
	s_add_i32 s38, s60, s3
	global_load_lds_dwordx4 v[214:215], off
	v_lshl_add_u64 v[214:215], s[36:37], 0, v[128:129]
	s_mov_b32 m0, s38
	s_nop 0
	global_load_lds_dwordx4 v[214:215], off
	v_lshl_add_u64 v[214:215], s[36:37], 0, v[130:131]
	s_add_i32 m0, s38, 0x2000
	s_nop 0
	global_load_lds_dwordx4 v[214:215], off
	v_lshl_add_u64 v[214:215], v[218:219], 0, s[16:17]
	s_mov_b32 m0, s48
	s_nop 0
	global_load_lds_dwordx4 v[214:215], off
	v_lshl_add_u64 v[214:215], v[220:221], 0, s[16:17]
	s_mov_b32 m0, s49
	s_nop 0
	global_load_lds_dwordx4 v[214:215], off
	s_waitcnt vmcnt(8)
	s_waitcnt lgkmcnt(0)
	s_barrier
	s_setprio 1
	s_waitcnt lgkmcnt(0)
	v_mfma_f32_16x16x32_bf16 v[60:63], v[140:143], v[180:183], v[60:63]
	v_mfma_f32_16x16x32_bf16 v[56:59], v[156:159], v[180:183], v[56:59]
	v_mfma_f32_16x16x32_bf16 v[44:47], v[140:143], v[188:191], v[44:47]
	v_mfma_f32_16x16x32_bf16 v[40:43], v[156:159], v[188:191], v[40:43]
	v_mfma_f32_16x16x32_bf16 v[28:31], v[140:143], v[196:199], v[28:31]
	v_mfma_f32_16x16x32_bf16 v[24:27], v[156:159], v[196:199], v[24:27]
	v_mfma_f32_16x16x32_bf16 v[12:15], v[140:143], v[206:209], v[12:15]
	v_mfma_f32_16x16x32_bf16 v[8:11], v[156:159], v[206:209], v[8:11]
	v_mfma_f32_16x16x32_bf16 v[60:63], v[152:155], v[184:187], v[60:63]
	v_mfma_f32_16x16x32_bf16 v[56:59], v[160:163], v[184:187], v[56:59]
	v_mfma_f32_16x16x32_bf16 v[44:47], v[152:155], v[192:195], v[44:47]
	v_mfma_f32_16x16x32_bf16 v[40:43], v[160:163], v[192:195], v[40:43]
	v_mfma_f32_16x16x32_bf16 v[28:31], v[152:155], v[202:205], v[28:31]
	v_mfma_f32_16x16x32_bf16 v[24:27], v[160:163], v[202:205], v[24:27]
	v_mfma_f32_16x16x32_bf16 v[12:15], v[152:155], v[210:213], v[12:15]
	v_mfma_f32_16x16x32_bf16 v[8:11], v[160:163], v[210:213], v[8:11]
	v_mfma_f32_16x16x32_bf16 v[52:55], v[164:167], v[180:183], v[52:55]
	v_mfma_f32_16x16x32_bf16 v[48:51], v[172:175], v[180:183], v[48:51]
	v_mfma_f32_16x16x32_bf16 v[36:39], v[164:167], v[188:191], v[36:39]
	v_mfma_f32_16x16x32_bf16 v[32:35], v[172:175], v[188:191], v[32:35]
	v_mfma_f32_16x16x32_bf16 v[20:23], v[164:167], v[196:199], v[20:23]
	v_mfma_f32_16x16x32_bf16 v[16:19], v[172:175], v[196:199], v[16:19]
	v_mfma_f32_16x16x32_bf16 v[4:7], v[164:167], v[206:209], v[4:7]
	v_mfma_f32_16x16x32_bf16 v[0:3], v[172:175], v[206:209], v[0:3]
	v_mfma_f32_16x16x32_bf16 v[52:55], v[168:171], v[184:187], v[52:55]
	v_mfma_f32_16x16x32_bf16 v[48:51], v[176:179], v[184:187], v[48:51]
	v_mfma_f32_16x16x32_bf16 v[36:39], v[168:171], v[192:195], v[36:39]
	v_mfma_f32_16x16x32_bf16 v[32:35], v[176:179], v[192:195], v[32:35]
	v_mfma_f32_16x16x32_bf16 v[20:23], v[168:171], v[202:205], v[20:23]
	v_mfma_f32_16x16x32_bf16 v[16:19], v[176:179], v[202:205], v[16:19]
	v_mfma_f32_16x16x32_bf16 v[4:7], v[168:171], v[210:213], v[4:7]
	v_mfma_f32_16x16x32_bf16 v[0:3], v[176:179], v[210:213], v[0:3]
	s_setprio 0
	s_barrier
	s_add_i32 s58, s58, 2
	s_add_u32 s34, s34, 0x100
	s_addc_u32 s35, s35, 0
	s_add_u32 s56, s56, 0x100
	s_addc_u32 s57, s57, 0
	s_cmp_gt_u32 s58, 29
	s_cbranch_scc0 .LBB0_455
	s_and_b64 vcc, exec, s[18:19]
	s_cbranch_vccz .LBB0_458
	s_barrier

.LBB0_495:
	v_add_u32_e32 v147, s53, v145
	ds_read_b128 v[148:151], v147
	ds_read_b128 v[152:155], v147 offset:1024
	ds_read_b128 v[156:159], v147 offset:2048
	ds_read_b128 v[160:163], v147 offset:3072
	v_add_u32_e32 v147, s54, v145
	s_add_u32 s34, s16, s30
	ds_read_b128 v[164:167], v147
	ds_read_b128 v[172:175], v147 offset:1024
	ds_read_b128 v[176:179], v147 offset:2048
	ds_read_b128 v[180:183], v147 offset:3072
	s_addc_u32 s35, s17, s31
	s_add_u32 s34, s34, 0x100
	s_addc_u32 s35, s35, 0
	s_add_u32 s59, s27, s30
	s_addc_u32 s60, s55, s31
	s_cmpk_eq_i32 s30, 0xf00
	s_cselect_b32 s37, s21, s35
	s_cselect_b32 s36, s23, s34
	s_cselect_b32 s35, s56, s60
	s_cselect_b32 s34, s57, s59
	v_lshl_add_u64 v[168:169], v[140:141], 0, s[30:31]
	s_add_i32 m0, s40, 0xc000
	ds_read_b128 v[184:187], v146
	ds_read_b128 v[188:191], v146 offset:1024
	ds_read_b128 v[192:195], v146 offset:2048
	ds_read_b128 v[196:199], v146 offset:3072
	ds_read_b128 v[202:205], v146 offset:4096
	ds_read_b128 v[206:209], v146 offset:5120
	ds_read_b128 v[210:213], v146 offset:6144
	ds_read_b128 v[214:217], v146 offset:7168
	global_load_lds_dwordx4 v[168:169], off
	v_lshl_add_u64 v[168:169], v[142:143], 0, s[30:31]
	s_add_i32 m0, s40, 0xe000
	s_nop 0
	global_load_lds_dwordx4 v[168:169], off
	s_waitcnt vmcnt(8)
	s_waitcnt lgkmcnt(0)
	s_barrier
	s_setprio 1
	s_waitcnt lgkmcnt(0)
	v_mfma_f32_16x16x32_bf16 v[124:127], v[148:151], v[184:187], v[124:127]
	v_mfma_f32_16x16x32_bf16 v[120:123], v[156:159], v[184:187], v[120:123]
	v_mfma_f32_16x16x32_bf16 v[108:111], v[148:151], v[192:195], v[108:111]
	v_mfma_f32_16x16x32_bf16 v[104:107], v[156:159], v[192:195], v[104:107]
	v_mfma_f32_16x16x32_bf16 v[92:95], v[148:151], v[202:205], v[92:95]
	v_mfma_f32_16x16x32_bf16 v[88:91], v[156:159], v[202:205], v[88:91]
	v_mfma_f32_16x16x32_bf16 v[76:79], v[148:151], v[210:213], v[76:79]
	v_mfma_f32_16x16x32_bf16 v[72:75], v[156:159], v[210:213], v[72:75]
	v_mfma_f32_16x16x32_bf16 v[124:127], v[152:155], v[188:191], v[124:127]
	v_mfma_f32_16x16x32_bf16 v[120:123], v[160:163], v[188:191], v[120:123]
	v_mfma_f32_16x16x32_bf16 v[108:111], v[152:155], v[196:199], v[108:111]
	v_mfma_f32_16x16x32_bf16 v[104:107], v[160:163], v[196:199], v[104:107]
	v_mfma_f32_16x16x32_bf16 v[92:95], v[152:155], v[206:209], v[92:95]
	v_mfma_f32_16x16x32_bf16 v[88:91], v[160:163], v[206:209], v[88:91]
	v_mfma_f32_16x16x32_bf16 v[76:79], v[152:155], v[214:217], v[76:79]
	v_mfma_f32_16x16x32_bf16 v[72:75], v[160:163], v[214:217], v[72:75]
	v_mfma_f32_16x16x32_bf16 v[116:119], v[164:167], v[184:187], v[116:119]
	v_mfma_f32_16x16x32_bf16 v[112:115], v[176:179], v[184:187], v[112:115]
	v_mfma_f32_16x16x32_bf16 v[100:103], v[164:167], v[192:195], v[100:103]
	v_mfma_f32_16x16x32_bf16 v[96:99], v[176:179], v[192:195], v[96:99]
	v_mfma_f32_16x16x32_bf16 v[84:87], v[164:167], v[202:205], v[84:87]
	v_mfma_f32_16x16x32_bf16 v[80:83], v[176:179], v[202:205], v[80:83]
	v_mfma_f32_16x16x32_bf16 v[68:71], v[164:167], v[210:213], v[68:71]
	v_mfma_f32_16x16x32_bf16 v[64:67], v[176:179], v[210:213], v[64:67]
	v_mfma_f32_16x16x32_bf16 v[116:119], v[172:175], v[188:191], v[116:119]
	v_mfma_f32_16x16x32_bf16 v[112:115], v[180:183], v[188:191], v[112:115]
	v_mfma_f32_16x16x32_bf16 v[100:103], v[172:175], v[196:199], v[100:103]
	v_mfma_f32_16x16x32_bf16 v[96:99], v[180:183], v[196:199], v[96:99]
	v_mfma_f32_16x16x32_bf16 v[84:87], v[172:175], v[206:209], v[84:87]
	v_mfma_f32_16x16x32_bf16 v[80:83], v[180:183], v[206:209], v[80:83]
	v_mfma_f32_16x16x32_bf16 v[68:71], v[172:175], v[214:217], v[68:71]
	v_mfma_f32_16x16x32_bf16 v[64:67], v[180:183], v[214:217], v[64:67]
	s_setprio 0
	s_barrier
	s_add_i32 s59, s53, s39
	v_lshl_add_u64 v[168:169], s[34:35], 0, v[128:129]
	s_mov_b32 m0, s59
	ds_read_b128 v[184:187], v146 offset:16384
	ds_read_b128 v[188:191], v146 offset:17408
	ds_read_b128 v[192:195], v146 offset:18432
	ds_read_b128 v[196:199], v146 offset:19456
	ds_read_b128 v[202:205], v146 offset:20480
	ds_read_b128 v[206:209], v146 offset:21504
	ds_read_b128 v[210:213], v146 offset:22528
	ds_read_b128 v[214:217], v146 offset:23552
	global_load_lds_dwordx4 v[168:169], off
	s_add_i32 m0, s59, 0x2000
	s_add_u32 s60, s34, 0x80000
	v_lshl_add_u64 v[218:219], s[34:35], 0, v[130:131]
	s_addc_u32 s61, s35, 0
	s_add_i32 s59, s54, s39
	global_load_lds_dwordx4 v[218:219], off
	v_lshl_add_u64 v[220:221], s[60:61], 0, v[128:129]
	s_mov_b32 m0, s59
	v_lshl_add_u64 v[222:223], s[36:37], 0, v[130:131]
	global_load_lds_dwordx4 v[220:221], off
	v_lshl_add_u64 v[220:221], s[60:61], 0, v[130:131]
	s_add_i32 m0, s59, 0x2000
	s_nop 0
	global_load_lds_dwordx4 v[220:221], off
	v_lshl_add_u64 v[220:221], s[36:37], 0, v[128:129]
	s_mov_b32 m0, s40
	s_nop 0
	global_load_lds_dwordx4 v[220:221], off
	s_mov_b32 m0, s41
	s_nop 0
	global_load_lds_dwordx4 v[222:223], off
	s_waitcnt vmcnt(8)
	s_waitcnt lgkmcnt(0)
	s_barrier
	s_setprio 1
	s_waitcnt lgkmcnt(0)
	v_mfma_f32_16x16x32_bf16 v[60:63], v[148:151], v[184:187], v[60:63]
	v_mfma_f32_16x16x32_bf16 v[56:59], v[156:159], v[184:187], v[56:59]
	v_mfma_f32_16x16x32_bf16 v[44:47], v[148:151], v[192:195], v[44:47]
	v_mfma_f32_16x16x32_bf16 v[40:43], v[156:159], v[192:195], v[40:43]
	v_mfma_f32_16x16x32_bf16 v[28:31], v[148:151], v[202:205], v[28:31]
	v_mfma_f32_16x16x32_bf16 v[24:27], v[156:159], v[202:205], v[24:27]
	v_mfma_f32_16x16x32_bf16 v[12:15], v[148:151], v[210:213], v[12:15]
	v_mfma_f32_16x16x32_bf16 v[8:11], v[156:159], v[210:213], v[8:11]
	v_mfma_f32_16x16x32_bf16 v[60:63], v[152:155], v[188:191], v[60:63]
	v_mfma_f32_16x16x32_bf16 v[56:59], v[160:163], v[188:191], v[56:59]
	v_mfma_f32_16x16x32_bf16 v[44:47], v[152:155], v[196:199], v[44:47]
	v_mfma_f32_16x16x32_bf16 v[40:43], v[160:163], v[196:199], v[40:43]
	v_mfma_f32_16x16x32_bf16 v[28:31], v[152:155], v[206:209], v[28:31]
	v_mfma_f32_16x16x32_bf16 v[24:27], v[160:163], v[206:209], v[24:27]
	v_mfma_f32_16x16x32_bf16 v[12:15], v[152:155], v[214:217], v[12:15]
	v_mfma_f32_16x16x32_bf16 v[8:11], v[160:163], v[214:217], v[8:11]
	v_mfma_f32_16x16x32_bf16 v[52:55], v[164:167], v[184:187], v[52:55]
	v_mfma_f32_16x16x32_bf16 v[48:51], v[176:179], v[184:187], v[48:51]
	v_mfma_f32_16x16x32_bf16 v[36:39], v[164:167], v[192:195], v[36:39]
	v_mfma_f32_16x16x32_bf16 v[32:35], v[176:179], v[192:195], v[32:35]
	v_mfma_f32_16x16x32_bf16 v[20:23], v[164:167], v[202:205], v[20:23]
	v_mfma_f32_16x16x32_bf16 v[16:19], v[176:179], v[202:205], v[16:19]
	v_mfma_f32_16x16x32_bf16 v[4:7], v[164:167], v[210:213], v[4:7]
	v_mfma_f32_16x16x32_bf16 v[0:3], v[176:179], v[210:213], v[0:3]
	v_mfma_f32_16x16x32_bf16 v[52:55], v[172:175], v[188:191], v[52:55]
	v_mfma_f32_16x16x32_bf16 v[48:51], v[180:183], v[188:191], v[48:51]
	v_mfma_f32_16x16x32_bf16 v[36:39], v[172:175], v[196:199], v[36:39]
	v_mfma_f32_16x16x32_bf16 v[32:35], v[180:183], v[196:199], v[32:35]
	v_mfma_f32_16x16x32_bf16 v[20:23], v[172:175], v[206:209], v[20:23]
	v_mfma_f32_16x16x32_bf16 v[16:19], v[180:183], v[206:209], v[16:19]
	v_mfma_f32_16x16x32_bf16 v[4:7], v[172:175], v[214:217], v[4:7]
	v_mfma_f32_16x16x32_bf16 v[0:3], v[180:183], v[214:217], v[0:3]
	s_setprio 0
	s_barrier
	s_add_i32 s59, 0, 0x18000
	v_add_u32_e32 v147, s59, v145
	s_add_i32 s60, 0, 0x1c000
	ds_read_b128 v[148:151], v147
	ds_read_b128 v[152:155], v147 offset:1024
	ds_read_b128 v[156:159], v147 offset:2048
	ds_read_b128 v[160:163], v147 offset:3072
	v_add_u32_e32 v147, s60, v145
	ds_read_b128 v[164:167], v147
	ds_read_b128 v[172:175], v147 offset:1024
	ds_read_b128 v[176:179], v147 offset:2048
	ds_read_b128 v[180:183], v147 offset:3072
	s_add_u32 s36, s36, 0x80000
	s_addc_u32 s37, s37, 0
	s_mov_b32 m0, s43
	v_lshl_add_u64 v[224:225], s[36:37], 0, v[128:129]
	ds_read_b128 v[184:187], v146 offset:32768
	ds_read_b128 v[188:191], v146 offset:33792
	ds_read_b128 v[192:195], v146 offset:34816
	ds_read_b128 v[196:199], v146 offset:35840
	ds_read_b128 v[202:205], v146 offset:36864
	ds_read_b128 v[206:209], v146 offset:37888
	ds_read_b128 v[210:213], v146 offset:38912
	ds_read_b128 v[214:217], v146 offset:39936
	global_load_lds_dwordx4 v[224:225], off
	v_lshl_add_u64 v[224:225], s[36:37], 0, v[130:131]
	s_mov_b32 m0, s48
	s_nop 0
	global_load_lds_dwordx4 v[224:225], off
	s_waitcnt vmcnt(8)
	s_waitcnt lgkmcnt(0)
	s_barrier
	s_setprio 1
	s_waitcnt lgkmcnt(0)
	v_mfma_f32_16x16x32_bf16 v[124:127], v[148:151], v[184:187], v[124:127]
	v_mfma_f32_16x16x32_bf16 v[120:123], v[156:159], v[184:187], v[120:123]
	v_mfma_f32_16x16x32_bf16 v[108:111], v[148:151], v[192:195], v[108:111]
	v_mfma_f32_16x16x32_bf16 v[104:107], v[156:159], v[192:195], v[104:107]
	v_mfma_f32_16x16x32_bf16 v[92:95], v[148:151], v[202:205], v[92:95]
	v_mfma_f32_16x16x32_bf16 v[88:91], v[156:159], v[202:205], v[88:91]
	v_mfma_f32_16x16x32_bf16 v[76:79], v[148:151], v[210:213], v[76:79]
	v_mfma_f32_16x16x32_bf16 v[72:75], v[156:159], v[210:213], v[72:75]
	v_mfma_f32_16x16x32_bf16 v[124:127], v[152:155], v[188:191], v[124:127]
	v_mfma_f32_16x16x32_bf16 v[120:123], v[160:163], v[188:191], v[120:123]
	v_mfma_f32_16x16x32_bf16 v[108:111], v[152:155], v[196:199], v[108:111]
	v_mfma_f32_16x16x32_bf16 v[104:107], v[160:163], v[196:199], v[104:107]
	v_mfma_f32_16x16x32_bf16 v[92:95], v[152:155], v[206:209], v[92:95]
	v_mfma_f32_16x16x32_bf16 v[88:91], v[160:163], v[206:209], v[88:91]
	v_mfma_f32_16x16x32_bf16 v[76:79], v[152:155], v[214:217], v[76:79]
	v_mfma_f32_16x16x32_bf16 v[72:75], v[160:163], v[214:217], v[72:75]
	v_mfma_f32_16x16x32_bf16 v[116:119], v[164:167], v[184:187], v[116:119]
	v_mfma_f32_16x16x32_bf16 v[112:115], v[176:179], v[184:187], v[112:115]
	v_mfma_f32_16x16x32_bf16 v[100:103], v[164:167], v[192:195], v[100:103]
	v_mfma_f32_16x16x32_bf16 v[96:99], v[176:179], v[192:195], v[96:99]
	v_mfma_f32_16x16x32_bf16 v[84:87], v[164:167], v[202:205], v[84:87]
	v_mfma_f32_16x16x32_bf16 v[80:83], v[176:179], v[202:205], v[80:83]
	v_mfma_f32_16x16x32_bf16 v[68:71], v[164:167], v[210:213], v[68:71]
	v_mfma_f32_16x16x32_bf16 v[64:67], v[176:179], v[210:213], v[64:67]
	v_mfma_f32_16x16x32_bf16 v[116:119], v[172:175], v[188:191], v[116:119]
	v_mfma_f32_16x16x32_bf16 v[112:115], v[180:183], v[188:191], v[112:115]
	v_mfma_f32_16x16x32_bf16 v[100:103], v[172:175], v[196:199], v[100:103]
	v_mfma_f32_16x16x32_bf16 v[96:99], v[180:183], v[196:199], v[96:99]
	v_mfma_f32_16x16x32_bf16 v[84:87], v[172:175], v[206:209], v[84:87]
	v_mfma_f32_16x16x32_bf16 v[80:83], v[180:183], v[206:209], v[80:83]
	v_mfma_f32_16x16x32_bf16 v[68:71], v[172:175], v[214:217], v[68:71]
	v_mfma_f32_16x16x32_bf16 v[64:67], v[180:183], v[214:217], v[64:67]
	s_setprio 0
	s_barrier
	s_add_i32 s36, s59, s39
	v_lshl_add_u64 v[168:169], v[168:169], 0, s[18:19]
	s_mov_b32 m0, s36
	ds_read_b128 v[184:187], v146 offset:49152
	ds_read_b128 v[188:191], v146 offset:50176
	ds_read_b128 v[192:195], v146 offset:51200
	ds_read_b128 v[196:199], v146 offset:52224
	ds_read_b128 v[202:205], v146 offset:53248
	ds_read_b128 v[206:209], v146 offset:54272
	ds_read_b128 v[210:213], v146 offset:55296
	ds_read_b128 v[214:217], v146 offset:56320
	global_load_lds_dwordx4 v[168:169], off
	s_add_i32 m0, s36, 0x2000
	s_add_u32 s34, s34, 0x80080
	v_lshl_add_u64 v[168:169], v[218:219], 0, s[18:19]
	s_addc_u32 s35, s35, 0
	s_add_i32 s36, s60, s39
	global_load_lds_dwordx4 v[168:169], off
	v_lshl_add_u64 v[168:169], s[34:35], 0, v[128:129]
	s_mov_b32 m0, s36
	s_nop 0
	global_load_lds_dwordx4 v[168:169], off
	v_lshl_add_u64 v[168:169], s[34:35], 0, v[130:131]
	s_add_i32 m0, s36, 0x2000
	s_nop 0
	global_load_lds_dwordx4 v[168:169], off
	v_lshl_add_u64 v[168:169], v[220:221], 0, s[18:19]
	s_mov_b32 m0, s49
	s_nop 0
	global_load_lds_dwordx4 v[168:169], off
	v_lshl_add_u64 v[168:169], v[222:223], 0, s[18:19]
	s_mov_b32 m0, s50
	s_nop 0
	global_load_lds_dwordx4 v[168:169], off
	s_waitcnt vmcnt(8)
	s_waitcnt lgkmcnt(0)
	s_barrier
	s_setprio 1
	s_waitcnt lgkmcnt(0)
	v_mfma_f32_16x16x32_bf16 v[60:63], v[148:151], v[184:187], v[60:63]
	v_mfma_f32_16x16x32_bf16 v[56:59], v[156:159], v[184:187], v[56:59]
	v_mfma_f32_16x16x32_bf16 v[44:47], v[148:151], v[192:195], v[44:47]
	v_mfma_f32_16x16x32_bf16 v[40:43], v[156:159], v[192:195], v[40:43]
	v_mfma_f32_16x16x32_bf16 v[28:31], v[148:151], v[202:205], v[28:31]
	v_mfma_f32_16x16x32_bf16 v[24:27], v[156:159], v[202:205], v[24:27]
	v_mfma_f32_16x16x32_bf16 v[12:15], v[148:151], v[210:213], v[12:15]
	v_mfma_f32_16x16x32_bf16 v[8:11], v[156:159], v[210:213], v[8:11]
	v_mfma_f32_16x16x32_bf16 v[60:63], v[152:155], v[188:191], v[60:63]
	v_mfma_f32_16x16x32_bf16 v[56:59], v[160:163], v[188:191], v[56:59]
	v_mfma_f32_16x16x32_bf16 v[44:47], v[152:155], v[196:199], v[44:47]
	v_mfma_f32_16x16x32_bf16 v[40:43], v[160:163], v[196:199], v[40:43]
	v_mfma_f32_16x16x32_bf16 v[28:31], v[152:155], v[206:209], v[28:31]
	v_mfma_f32_16x16x32_bf16 v[24:27], v[160:163], v[206:209], v[24:27]
	v_mfma_f32_16x16x32_bf16 v[12:15], v[152:155], v[214:217], v[12:15]
	v_mfma_f32_16x16x32_bf16 v[8:11], v[160:163], v[214:217], v[8:11]
	v_mfma_f32_16x16x32_bf16 v[52:55], v[164:167], v[184:187], v[52:55]
	v_mfma_f32_16x16x32_bf16 v[48:51], v[176:179], v[184:187], v[48:51]
	v_mfma_f32_16x16x32_bf16 v[36:39], v[164:167], v[192:195], v[36:39]
	v_mfma_f32_16x16x32_bf16 v[32:35], v[176:179], v[192:195], v[32:35]
	v_mfma_f32_16x16x32_bf16 v[20:23], v[164:167], v[202:205], v[20:23]
	v_mfma_f32_16x16x32_bf16 v[16:19], v[176:179], v[202:205], v[16:19]
	v_mfma_f32_16x16x32_bf16 v[4:7], v[164:167], v[210:213], v[4:7]
	v_mfma_f32_16x16x32_bf16 v[0:3], v[176:179], v[210:213], v[0:3]
	v_mfma_f32_16x16x32_bf16 v[52:55], v[172:175], v[188:191], v[52:55]
	v_mfma_f32_16x16x32_bf16 v[48:51], v[180:183], v[188:191], v[48:51]
	v_mfma_f32_16x16x32_bf16 v[36:39], v[172:175], v[196:199], v[36:39]
	v_mfma_f32_16x16x32_bf16 v[32:35], v[180:183], v[196:199], v[32:35]
	v_mfma_f32_16x16x32_bf16 v[20:23], v[172:175], v[206:209], v[20:23]
	v_mfma_f32_16x16x32_bf16 v[16:19], v[180:183], v[206:209], v[16:19]
	v_mfma_f32_16x16x32_bf16 v[4:7], v[172:175], v[214:217], v[4:7]
	v_mfma_f32_16x16x32_bf16 v[0:3], v[180:183], v[214:217], v[0:3]
	s_setprio 0
	s_barrier
	s_add_i32 s58, s58, 2
	s_add_u32 s30, s30, 0x100
	s_addc_u32 s31, s31, 0
	s_cmp_gt_u32 s58, 29
	s_cbranch_scc0 .LBB0_495
	s_add_u32 s30, s27, 0xffffff00
	s_addc_u32 s31, s55, -1
	s_andn2_b64 vcc, exec, s[4:5]
	s_cbranch_vccnz .LBB0_498
	v_mov_b32_e32 v0, 0
	s_mov_b32 s51, s20
	s_mov_b32 s14, s22
	s_mov_b64 s[16:17], s[28:29]
	s_mov_b32 s52, s26
	v_mov_b32_e32 v1, v0
	v_mov_b32_e32 v2, v0
	v_mov_b32_e32 v3, v0
	v_mov_b32_e32 v4, v0
	v_mov_b32_e32 v5, v0
	v_mov_b32_e32 v6, v0
	v_mov_b32_e32 v7, v0
	v_mov_b32_e32 v16, v0
	v_mov_b32_e32 v17, v0
	v_mov_b32_e32 v18, v0
	v_mov_b32_e32 v19, v0
	v_mov_b32_e32 v20, v0
	v_mov_b32_e32 v21, v0
	v_mov_b32_e32 v22, v0
	v_mov_b32_e32 v23, v0
	v_mov_b32_e32 v32, v0
	v_mov_b32_e32 v33, v0
	v_mov_b32_e32 v34, v0
	v_mov_b32_e32 v35, v0
	v_mov_b32_e32 v36, v0
	v_mov_b32_e32 v37, v0
	v_mov_b32_e32 v38, v0
	v_mov_b32_e32 v39, v0
	v_mov_b32_e32 v48, v0
	v_mov_b32_e32 v49, v0
	v_mov_b32_e32 v50, v0
	v_mov_b32_e32 v51, v0
	v_mov_b32_e32 v52, v0
	v_mov_b32_e32 v53, v0
	v_mov_b32_e32 v54, v0
	v_mov_b32_e32 v55, v0
	v_mov_b32_e32 v8, v0
	v_mov_b32_e32 v9, v0
	v_mov_b32_e32 v10, v0
	v_mov_b32_e32 v11, v0
	v_mov_b32_e32 v12, v0
	v_mov_b32_e32 v13, v0
	v_mov_b32_e32 v14, v0
	v_mov_b32_e32 v15, v0
	v_mov_b32_e32 v24, v0
	v_mov_b32_e32 v25, v0
	v_mov_b32_e32 v26, v0
	v_mov_b32_e32 v27, v0
	v_mov_b32_e32 v28, v0
	v_mov_b32_e32 v29, v0
	v_mov_b32_e32 v30, v0
	v_mov_b32_e32 v31, v0
	v_mov_b32_e32 v40, v0
	v_mov_b32_e32 v41, v0
	v_mov_b32_e32 v42, v0
	v_mov_b32_e32 v43, v0
	v_mov_b32_e32 v44, v0
	v_mov_b32_e32 v45, v0
	v_mov_b32_e32 v46, v0
	v_mov_b32_e32 v47, v0
	v_mov_b32_e32 v56, v0
	v_mov_b32_e32 v57, v0
	v_mov_b32_e32 v58, v0
	v_mov_b32_e32 v59, v0
	v_mov_b32_e32 v60, v0
	v_mov_b32_e32 v61, v0
	v_mov_b32_e32 v62, v0
	v_mov_b32_e32 v63, v0
	v_mov_b32_e32 v64, v0
	v_mov_b32_e32 v65, v0
	v_mov_b32_e32 v66, v0
	v_mov_b32_e32 v67, v0
	v_mov_b32_e32 v68, v0
	v_mov_b32_e32 v69, v0
	v_mov_b32_e32 v70, v0
	v_mov_b32_e32 v71, v0
	v_mov_b32_e32 v80, v0
	v_mov_b32_e32 v81, v0
	v_mov_b32_e32 v82, v0
	v_mov_b32_e32 v83, v0
	v_mov_b32_e32 v84, v0
	v_mov_b32_e32 v85, v0
	v_mov_b32_e32 v86, v0
	v_mov_b32_e32 v87, v0
	v_mov_b32_e32 v96, v0
	v_mov_b32_e32 v97, v0
	v_mov_b32_e32 v98, v0
	v_mov_b32_e32 v99, v0
	v_mov_b32_e32 v100, v0
	v_mov_b32_e32 v101, v0
	v_mov_b32_e32 v102, v0
	v_mov_b32_e32 v103, v0
	v_mov_b32_e32 v112, v0
	v_mov_b32_e32 v113, v0
	v_mov_b32_e32 v114, v0
	v_mov_b32_e32 v115, v0
	v_mov_b32_e32 v116, v0
	v_mov_b32_e32 v117, v0
	v_mov_b32_e32 v118, v0
	v_mov_b32_e32 v119, v0
	v_mov_b32_e32 v72, v0
	v_mov_b32_e32 v73, v0
	v_mov_b32_e32 v74, v0
	v_mov_b32_e32 v75, v0
	v_mov_b32_e32 v76, v0
	v_mov_b32_e32 v77, v0
	v_mov_b32_e32 v78, v0
	v_mov_b32_e32 v79, v0
	v_mov_b32_e32 v88, v0
	v_mov_b32_e32 v89, v0
	v_mov_b32_e32 v90, v0
	v_mov_b32_e32 v91, v0
	v_mov_b32_e32 v92, v0
	v_mov_b32_e32 v93, v0
	v_mov_b32_e32 v94, v0
	v_mov_b32_e32 v95, v0
	v_mov_b32_e32 v104, v0
	v_mov_b32_e32 v105, v0
	v_mov_b32_e32 v106, v0
	v_mov_b32_e32 v107, v0
	v_mov_b32_e32 v108, v0
	v_mov_b32_e32 v109, v0
	v_mov_b32_e32 v110, v0
	v_mov_b32_e32 v111, v0
	v_mov_b32_e32 v120, v0
	v_mov_b32_e32 v121, v0
	v_mov_b32_e32 v122, v0
	v_mov_b32_e32 v123, v0
	v_mov_b32_e32 v124, v0
	v_mov_b32_e32 v125, v0
	v_mov_b32_e32 v126, v0
	v_mov_b32_e32 v127, v0
	s_andn2_b64 vcc, exec, s[0:1]
	s_cbranch_vccnz .LBB0_499
	s_branch .LBB0_500
